# attention map-1 epilogue: DPP moves for the xor-1/2/4 lane adds of the row sums of squares instead of LDS permutes
# speedup vs baseline: 1.0048x; 1.0027x over previous
.LBB0_383:
	v_add_f32_e32 v97, v80, v81
	v_add_f32_e32 v97, v82, v97
	v_add_f32_e32 v97, v83, v97
	v_add_f32_e32 v97, v84, v97
	v_add_f32_e32 v97, v85, v97
	v_add_f32_e32 v97, v86, v97
	v_add_f32_e32 v97, v87, v97
	v_add_f32_e32 v97, v88, v97
	v_add_f32_e32 v97, v89, v97
	v_add_f32_e32 v97, v90, v97
	v_add_f32_e32 v97, v91, v97
	v_add_f32_e32 v97, v92, v97
	v_add_f32_e32 v97, v93, v97
	v_add_f32_e32 v97, v94, v97
	v_add_f32_e32 v97, v95, v97
	v_add_f32_e32 v97, v97, v64
	v_add_f32_e32 v97, v65, v97
	v_add_f32_e32 v97, v66, v97
	v_add_f32_e32 v97, v67, v97
	v_add_f32_e32 v97, v68, v97
	v_add_f32_e32 v97, v69, v97
	v_add_f32_e32 v97, v70, v97
	v_add_f32_e32 v97, v71, v97
	v_add_f32_e32 v97, v72, v97
	v_add_f32_e32 v97, v73, v97
	v_add_f32_e32 v97, v74, v97
	v_add_f32_e32 v97, v75, v97
	v_add_f32_e32 v97, v76, v97
	v_add_f32_e32 v97, v77, v97
	v_add_f32_e32 v97, v78, v97
	v_add_f32_e32 v97, v79, v97
	v_add_f32_e32 v97, v112, v97
	v_cvt_pk_bf16_f32 v64, v64, v65
	v_lshl_add_u32 v98, s66, 1, v244
	v_cvt_pk_bf16_f32 v80, v80, v81
	v_cvt_pk_bf16_f32 v81, v82, v83
	v_cvt_pk_bf16_f32 v82, v84, v85
	v_cvt_pk_bf16_f32 v83, v86, v87
	v_cvt_pk_bf16_f32 v84, v88, v89
	v_cvt_pk_bf16_f32 v85, v90, v91
	v_cvt_pk_bf16_f32 v86, v92, v93
	v_cvt_pk_bf16_f32 v87, v94, v95
	v_cvt_pk_bf16_f32 v65, v66, v67
	v_cvt_pk_bf16_f32 v66, v68, v69
	v_cvt_pk_bf16_f32 v67, v70, v71
	v_cvt_pk_bf16_f32 v68, v72, v73
	v_cvt_pk_bf16_f32 v69, v74, v75
	v_cvt_pk_bf16_f32 v70, v76, v77
	v_cvt_pk_bf16_f32 v71, v78, v79
	v_add_u32_e32 v98, 0x6000, v98
	ds_read_b64_tr_b16 v[72:73],v98 offset:0
	ds_read_b64_tr_b16 v[74:75],v98 offset:512
	ds_read_b64_tr_b16 v[76:77],v98 offset:1024
	ds_read_b64_tr_b16 v[78:79],v98 offset:1536
	ds_read_b64_tr_b16 v[88:89],v98 offset:2048
	ds_read_b64_tr_b16 v[90:91],v98 offset:2560
	ds_read_b64_tr_b16 v[92:93],v98 offset:3072
	ds_read_b64_tr_b16 v[94:95],v98 offset:3584
	s_waitcnt lgkmcnt(0)
	s_nop 0
	v_mfma_f32_32x32x16_bf16 v[32:47], v[80:83], v[72:75], v[32:47]
	ds_read_b64_tr_b16 v[72:73],v98 offset:4096
	ds_read_b64_tr_b16 v[74:75],v98 offset:4608
	v_mfma_f32_32x32x16_bf16 v[32:47], v[84:87], v[76:79], v[32:47]
	ds_read_b64_tr_b16 v[76:77],v98 offset:5120
	ds_read_b64_tr_b16 v[78:79],v98 offset:5632
	v_mfma_f32_32x32x16_bf16 v[32:47], v[64:67], v[88:91], v[32:47]
	ds_read_b64_tr_b16 v[88:89],v98 offset:6144
	ds_read_b64_tr_b16 v[90:91],v98 offset:6656
	v_mfma_f32_32x32x16_bf16 v[32:47], v[68:71], v[92:95], v[32:47]
	ds_read_b64_tr_b16 v[92:93],v98 offset:7168
	ds_read_b64_tr_b16 v[94:95],v98 offset:7680
	s_waitcnt lgkmcnt(0)
	v_mfma_f32_32x32x16_bf16 v[48:63], v[80:83], v[72:75], v[48:63]
	ds_read_b64_tr_b16 v[72:73],v98 offset:8192
	ds_read_b64_tr_b16 v[74:75],v98 offset:8704
	v_mfma_f32_32x32x16_bf16 v[48:63], v[84:87], v[76:79], v[48:63]
	ds_read_b64_tr_b16 v[76:77],v98 offset:9216
	ds_read_b64_tr_b16 v[78:79],v98 offset:9728
	v_mfma_f32_32x32x16_bf16 v[48:63], v[64:67], v[88:91], v[48:63]
	ds_read_b64_tr_b16 v[88:89],v98 offset:10240
	ds_read_b64_tr_b16 v[90:91],v98 offset:10752
	v_mfma_f32_32x32x16_bf16 v[48:63], v[68:71], v[92:95], v[48:63]
	ds_read_b64_tr_b16 v[92:93],v98 offset:11264
	ds_read_b64_tr_b16 v[94:95],v98 offset:11776
	s_waitcnt lgkmcnt(0)
	v_mfma_f32_32x32x16_bf16 v[16:31], v[80:83], v[72:75], v[16:31]
	ds_read_b64_tr_b16 v[72:73],v98 offset:12288
	ds_read_b64_tr_b16 v[74:75],v98 offset:12800
	v_mfma_f32_32x32x16_bf16 v[16:31], v[84:87], v[76:79], v[16:31]
	ds_read_b64_tr_b16 v[76:77],v98 offset:13312
	ds_read_b64_tr_b16 v[78:79],v98 offset:13824
	v_mfma_f32_32x32x16_bf16 v[16:31], v[64:67], v[88:91], v[16:31]
	ds_read_b64_tr_b16 v[88:89],v98 offset:14336
	ds_read_b64_tr_b16 v[90:91],v98 offset:14848
	v_mfma_f32_32x32x16_bf16 v[16:31], v[68:71], v[92:95], v[16:31]
	ds_read_b64_tr_b16 v[92:93],v98 offset:15360
	ds_read_b64_tr_b16 v[94:95],v98 offset:15872
	s_waitcnt lgkmcnt(0)
	v_mfma_f32_32x32x16_bf16 v[0:15], v[80:83], v[72:75], v[0:15]
	v_cmp_gt_u32_e32 vcc, 32, v239
	v_mfma_f32_32x32x16_bf16 v[0:15], v[84:87], v[76:79], v[0:15]
	v_mfma_f32_32x32x16_bf16 v[0:15], v[64:67], v[88:91], v[0:15]
	v_mov_b32_e32 v64, v97
	s_nop 1
	v_permlane32_swap_b32_e32 v97, v64
	v_mfma_f32_32x32x16_bf16 v[0:15], v[68:71], v[92:95], v[0:15]
	s_and_saveexec_b64 s[2:3], vcc
	v_add_f32_e32 v64, v97, v64
	ds_write_b32 v243, v64 offset:128
	s_or_b64 exec, exec, s[2:3]
	s_waitcnt lgkmcnt(0)
	ds_read_b128 v[64:67], v96 offset:128
	ds_read_b128 v[68:71], v96 offset:160
	s_lshl_b32 s2, s55, 7
	s_lshl_b64 s[4:5], s[78:79], 12
	s_add_u32 s4, s52, s4
	s_waitcnt lgkmcnt(1)
	v_rcp_f32_e32 v72, v64
	v_rcp_f32_e32 v73, v65
	v_rcp_f32_e32 v74, v66
	v_rcp_f32_e32 v75, v67
	s_waitcnt lgkmcnt(0)
	v_rcp_f32_e32 v76, v68
	ds_read_b128 v[64:67], v96 offset:192
	v_rcp_f32_e32 v77, v69
	v_rcp_f32_e32 v78, v70
	v_rcp_f32_e32 v79, v71
	ds_read_b128 v[68:71], v96 offset:224
	s_addc_u32 s5, s53, s5
	s_ashr_i32 s3, s2, 31
	s_lshl_b64 s[2:3], s[2:3], 1
	s_waitcnt lgkmcnt(1)
	v_rcp_f32_e32 v64, v64
	v_rcp_f32_e32 v65, v65
	v_rcp_f32_e32 v66, v66
	v_rcp_f32_e32 v67, v67
	s_waitcnt lgkmcnt(0)
	v_rcp_f32_e32 v68, v68
	v_rcp_f32_e32 v69, v69
	v_rcp_f32_e32 v70, v70
	v_rcp_f32_e32 v71, v71
	s_add_u32 s2, s4, s2
	s_addc_u32 s3, s5, s3
	s_bitcmp1_b32 s55, 0
	s_cselect_b64 s[14:15], -1, 0
	v_lshlrev_b32_e32 v165, 7, v242
	s_mov_b64 s[4:5], -1
	s_and_b64 vcc, exec, s[14:15]
	v_lshl_add_u32 v122, v241, 1, s88
	v_mul_f32_e32 v167, v32, v72
	v_mul_f32_e32 v166, v48, v72
	v_mul_f32_e32 v164, v33, v73
	v_mul_f32_e32 v163, v49, v73
	v_mul_f32_e32 v162, v34, v74
	v_mul_f32_e32 v161, v50, v74
	v_mul_f32_e32 v160, v35, v75
	v_mul_f32_e32 v159, v51, v75
	v_or_b32_e32 v157, 0x400, v165
	v_mul_f32_e32 v158, v36, v76
	v_mul_f32_e32 v156, v52, v76
	v_or_b32_e32 v154, 0x480, v165
	v_mul_f32_e32 v155, v37, v77
	v_mul_f32_e32 v153, v53, v77
	v_or_b32_e32 v151, 0x500, v165
	v_mul_f32_e32 v152, v38, v78
	v_mul_f32_e32 v150, v54, v78
	v_or_b32_e32 v148, 0x580, v165
	v_mul_f32_e32 v149, v39, v79
	v_mul_f32_e32 v147, v55, v79
	v_or_b32_e32 v145, 0x800, v165
	v_mul_f32_e32 v146, v40, v64
	v_mul_f32_e32 v144, v56, v64
	v_or_b32_e32 v142, 0x880, v165
	v_mul_f32_e32 v143, v41, v65
	v_mul_f32_e32 v141, v57, v65
	v_or_b32_e32 v139, 0x900, v165
	v_mul_f32_e32 v140, v42, v66
	v_mul_f32_e32 v138, v58, v66
	v_or_b32_e32 v136, 0x980, v165
	v_mul_f32_e32 v137, v43, v67
	v_mul_f32_e32 v135, v59, v67
	v_or_b32_e32 v133, 0xc00, v165
	v_mul_f32_e32 v134, v44, v68
	v_mul_f32_e32 v132, v60, v68
	v_or_b32_e32 v130, 0xc80, v165
	v_mul_f32_e32 v131, v45, v69
	v_mul_f32_e32 v129, v61, v69
	v_or_b32_e32 v127, 0xd00, v165
	v_mul_f32_e32 v128, v46, v70
	v_mul_f32_e32 v126, v62, v70
	v_or_b32_e32 v124, 0xd80, v165
	v_mul_f32_e32 v125, v47, v71
	v_mul_f32_e32 v123, v63, v71
	v_mul_f32_e32 v121, v16, v72
	v_mul_f32_e32 v120, v0, v72
	v_mul_f32_e32 v119, v17, v73
	v_mul_f32_e32 v118, v1, v73
	v_mul_f32_e32 v117, v18, v74
	v_mul_f32_e32 v116, v2, v74
	v_mul_f32_e32 v115, v19, v75
	v_mul_f32_e32 v114, v3, v75
	v_mul_f32_e32 v113, v20, v76
	v_mul_f32_e32 v112, v4, v76
	v_mul_f32_e32 v111, v21, v77
	v_mul_f32_e32 v110, v5, v77
	v_mul_f32_e32 v109, v22, v78
	v_mul_f32_e32 v108, v6, v78
	v_mul_f32_e32 v107, v23, v79
	v_mul_f32_e32 v106, v7, v79
	v_mul_f32_e32 v105, v24, v64
	v_mul_f32_e32 v104, v8, v64
	v_mul_f32_e32 v103, v25, v65
	v_mul_f32_e32 v102, v9, v65
	v_mul_f32_e32 v101, v26, v66
	v_mul_f32_e32 v100, v10, v66
	v_mul_f32_e32 v99, v27, v67
	v_mul_f32_e32 v98, v11, v67
	v_mul_f32_e32 v97, v28, v68
	v_mul_f32_e32 v96, v12, v68
	v_mul_f32_e32 v95, v29, v69
	v_mul_f32_e32 v94, v13, v69
	v_mul_f32_e32 v93, v30, v70
	v_mul_f32_e32 v92, v14, v70
	v_mul_f32_e32 v91, v31, v71
	v_mul_f32_e32 v90, v15, v71
	s_cbranch_vccz .LBB0_387
	v_and_b32_e32 v72, 56, v240
	v_lshlrev_b32_e32 v2, 4, v239
	v_lshlrev_b32_e32 v212, 1, v72
	v_and_b32_e32 v2, 0x380, v2
	s_movk_i32 s4, 0xff00
	v_add3_u32 v64, s88, v2, v212
	v_lshlrev_b32_e32 v2, 9, v239
	v_lshl_add_u64 v[24:25], s[2:3], 0, v[212:213]
	s_mov_b32 s5, -1
	v_and_b32_e32 v2, 0x7000, v2
	v_lshl_add_u64 v[0:1], v[24:25], 0, s[4:5]
	v_mov_b32_e32 v3, v213
	v_or_b32_e32 v28, 0x8000, v2
	v_mov_b32_e32 v29, v213
	v_lshl_add_u64 v[26:27], v[0:1], 0, v[2:3]
	v_lshl_add_u64 v[4:5], v[0:1], 0, v[28:29]
	v_or_b32_e32 v30, 0x10000, v2
	v_mov_b32_e32 v31, v213
	v_or_b32_e32 v48, 0x18000, v2
	v_mov_b32_e32 v49, v213
	global_load_dwordx4 v[32:35], v[26:27], off
	global_load_dwordx4 v[16:19], v[4:5], off
	v_lshl_add_u64 v[4:5], v[0:1], 0, v[30:31]
	v_lshl_add_u64 v[0:1], v[0:1], 0, v[48:49]
	global_load_dwordx4 v[8:11], v[4:5], off
	v_add_u32_e32 v50, v122, v165
	global_load_dwordx4 v[0:3], v[0:1], off
	v_cvt_pk_bf16_f32 v4, v167, s0
	ds_write_b16 v50, v4
	v_cvt_pk_bf16_f32 v4, v166, s0
	ds_write_b16 v50, v4 offset:64
	v_cvt_pk_bf16_f32 v4, v164, s0
	ds_write_b16 v50, v4 offset:128
	v_cvt_pk_bf16_f32 v4, v163, s0
	ds_write_b16 v50, v4 offset:192
	v_cvt_pk_bf16_f32 v4, v162, s0
	ds_write_b16 v50, v4 offset:256
	v_cvt_pk_bf16_f32 v4, v161, s0
	ds_write_b16 v50, v4 offset:320
	v_cvt_pk_bf16_f32 v4, v160, s0
	ds_write_b16 v50, v4 offset:384
	v_cvt_pk_bf16_f32 v4, v159, s0
	ds_write_b16 v50, v4 offset:448
	v_add_u32_e32 v51, v122, v157
	v_cvt_pk_bf16_f32 v4, v158, s0
	ds_write_b16 v51, v4
	v_cvt_pk_bf16_f32 v4, v156, s0
	ds_write_b16 v51, v4 offset:64
	v_add_u32_e32 v52, v122, v154
	v_cvt_pk_bf16_f32 v4, v155, s0
	ds_write_b16 v52, v4
	v_cvt_pk_bf16_f32 v4, v153, s0
	ds_write_b16 v52, v4 offset:64
	v_add_u32_e32 v53, v122, v151
	v_cvt_pk_bf16_f32 v4, v152, s0
	ds_write_b16 v53, v4
	v_cvt_pk_bf16_f32 v4, v150, s0
	ds_write_b16 v53, v4 offset:64
	v_add_u32_e32 v54, v122, v148
	v_cvt_pk_bf16_f32 v4, v149, s0
	ds_write_b16 v54, v4
	v_cvt_pk_bf16_f32 v4, v147, s0
	ds_write_b16 v54, v4 offset:64
	v_add_u32_e32 v55, v122, v145
	v_cvt_pk_bf16_f32 v4, v146, s0
	ds_write_b16 v55, v4
	v_cvt_pk_bf16_f32 v4, v144, s0
	ds_write_b16 v55, v4 offset:64
	v_add_u32_e32 v56, v122, v142
	v_cvt_pk_bf16_f32 v4, v143, s0
	ds_write_b16 v56, v4
	v_cvt_pk_bf16_f32 v4, v141, s0
	ds_write_b16 v56, v4 offset:64
	v_add_u32_e32 v57, v122, v139
	v_cvt_pk_bf16_f32 v4, v140, s0
	ds_write_b16 v57, v4
	v_cvt_pk_bf16_f32 v4, v138, s0
	ds_write_b16 v57, v4 offset:64
	v_add_u32_e32 v58, v122, v136
	v_cvt_pk_bf16_f32 v4, v137, s0
	ds_write_b16 v58, v4
	v_cvt_pk_bf16_f32 v4, v135, s0
	ds_write_b16 v58, v4 offset:64
	v_add_u32_e32 v59, v122, v133
	v_cvt_pk_bf16_f32 v4, v134, s0
	ds_write_b16 v59, v4
	v_cvt_pk_bf16_f32 v4, v132, s0
	ds_write_b16 v59, v4 offset:64
	v_add_u32_e32 v60, v122, v130
	v_cvt_pk_bf16_f32 v4, v131, s0
	ds_write_b16 v60, v4
	v_cvt_pk_bf16_f32 v4, v129, s0
	ds_write_b16 v60, v4 offset:64
	v_add_u32_e32 v61, v122, v127
	v_cvt_pk_bf16_f32 v4, v128, s0
	ds_write_b16 v61, v4
	v_cvt_pk_bf16_f32 v4, v126, s0
	ds_write_b16 v61, v4 offset:64
	v_add_u32_e32 v62, v122, v124
	v_cvt_pk_bf16_f32 v4, v125, s0
	ds_write_b16 v62, v4
	v_cvt_pk_bf16_f32 v4, v123, s0
	ds_write_b16 v62, v4 offset:64
	s_waitcnt lgkmcnt(0)
	ds_read_b128 v[36:39], v64
	ds_read_b128 v[20:23], v64 offset:1024
	ds_read_b128 v[12:15], v64 offset:2048
	ds_read_b128 v[4:7], v64 offset:3072
	s_waitcnt lgkmcnt(0)
	global_load_dwordx4 v[44:47], v[26:27], off offset:128
	s_movk_i32 s4, 0xff80
	s_mov_b32 s5, -1
	v_lshl_add_u64 v[24:25], v[24:25], 0, s[4:5]
	v_lshl_add_u64 v[26:27], v[24:25], 0, v[28:29]
	global_load_dwordx4 v[40:43], v[26:27], off
	v_lshl_add_u64 v[26:27], v[24:25], 0, v[30:31]
	global_load_dwordx4 v[28:31], v[26:27], off
	v_lshl_add_u64 v[24:25], v[24:25], 0, v[48:49]
	global_load_dwordx4 v[24:27], v[24:25], off
	v_cvt_pk_bf16_f32 v48, v121, s0
	ds_write_b16 v50, v48
	v_cvt_pk_bf16_f32 v48, v120, s0
	ds_write_b16 v50, v48 offset:64
	v_cvt_pk_bf16_f32 v48, v119, s0
	ds_write_b16 v50, v48 offset:128
	v_cvt_pk_bf16_f32 v48, v118, s0
	ds_write_b16 v50, v48 offset:192
	v_cvt_pk_bf16_f32 v48, v117, s0
	ds_write_b16 v50, v48 offset:256
	v_cvt_pk_bf16_f32 v48, v116, s0
	ds_write_b16 v50, v48 offset:320
	v_cvt_pk_bf16_f32 v48, v115, s0
	ds_write_b16 v50, v48 offset:384
	v_cvt_pk_bf16_f32 v48, v114, s0
	ds_write_b16 v50, v48 offset:448
	v_cvt_pk_bf16_f32 v48, v113, s0
	ds_write_b16 v51, v48
	v_cvt_pk_bf16_f32 v48, v112, s0
	ds_write_b16 v51, v48 offset:64
	v_cvt_pk_bf16_f32 v48, v111, s0
	ds_write_b16 v52, v48
	v_cvt_pk_bf16_f32 v48, v110, s0
	ds_write_b16 v52, v48 offset:64
	v_cvt_pk_bf16_f32 v48, v109, s0
	ds_write_b16 v53, v48
	v_cvt_pk_bf16_f32 v48, v108, s0
	ds_write_b16 v53, v48 offset:64
	v_cvt_pk_bf16_f32 v48, v107, s0
	ds_write_b16 v54, v48
	v_cvt_pk_bf16_f32 v48, v106, s0
	ds_write_b16 v54, v48 offset:64
	v_cvt_pk_bf16_f32 v48, v105, s0
	ds_write_b16 v55, v48
	v_cvt_pk_bf16_f32 v48, v104, s0
	ds_write_b16 v55, v48 offset:64
	v_cvt_pk_bf16_f32 v48, v103, s0
	ds_write_b16 v56, v48
	v_cvt_pk_bf16_f32 v48, v102, s0
	ds_write_b16 v56, v48 offset:64
	v_cvt_pk_bf16_f32 v48, v101, s0
	ds_write_b16 v57, v48
	v_cvt_pk_bf16_f32 v48, v100, s0
	ds_write_b16 v57, v48 offset:64
	v_cvt_pk_bf16_f32 v48, v99, s0
	ds_write_b16 v58, v48
	v_cvt_pk_bf16_f32 v48, v98, s0
	ds_write_b16 v58, v48 offset:64
	v_cvt_pk_bf16_f32 v48, v97, s0
	ds_write_b16 v59, v48
	v_cvt_pk_bf16_f32 v48, v96, s0
	ds_write_b16 v59, v48 offset:64
	v_cvt_pk_bf16_f32 v48, v95, s0
	ds_write_b16 v60, v48
	v_cvt_pk_bf16_f32 v48, v94, s0
	ds_write_b16 v60, v48 offset:64
	v_cvt_pk_bf16_f32 v48, v93, s0
	ds_write_b16 v61, v48
	v_cvt_pk_bf16_f32 v48, v92, s0
	ds_write_b16 v61, v48 offset:64
	v_cvt_pk_bf16_f32 v48, v91, s0
	ds_write_b16 v62, v48
	v_cvt_pk_bf16_f32 v48, v90, s0
	ds_write_b16 v62, v48 offset:64
	s_waitcnt lgkmcnt(0)
	ds_read_b128 v[50:53], v64
	v_lshlrev_b32_e32 v168, 2, v72
	s_waitcnt vmcnt(7)
	v_lshlrev_b32_e32 v172, 16, v35
	v_and_b32_e32 v173, 0xffff0000, v35
	v_lshlrev_b32_e32 v176, 16, v34
	s_waitcnt vmcnt(3)
	v_lshlrev_b32_e32 v49, 16, v45
	v_lshlrev_b32_e32 v48, 16, v44
	v_and_b32_e32 v45, 0xffff0000, v45
	v_and_b32_e32 v44, 0xffff0000, v44
	s_waitcnt lgkmcnt(0)
	v_lshlrev_b32_e32 v55, 16, v51
	v_lshlrev_b32_e32 v54, 16, v50
	v_and_b32_e32 v57, 0xffff0000, v51
	v_and_b32_e32 v56, 0xffff0000, v50
	v_pk_fma_f32 v[50:51], s[10:11], v[54:55], v[48:49] neg_lo:[1,0,0] neg_hi:[1,0,0]
	v_pk_fma_f32 v[48:49], s[10:11], v[56:57], v[44:45] neg_lo:[1,0,0] neg_hi:[1,0,0]
	v_and_b32_e32 v55, 0xffff0000, v47
	v_pk_mul_f32 v[44:45], v[48:49], v[48:49]
	v_and_b32_e32 v54, 0xffff0000, v46
	v_pk_fma_f32 v[86:87], v[50:51], v[50:51], v[44:45]
	v_lshlrev_b32_e32 v45, 16, v47
	v_lshlrev_b32_e32 v44, 16, v46
	v_lshlrev_b32_e32 v47, 16, v53
	v_lshlrev_b32_e32 v46, 16, v52
	v_and_b32_e32 v53, 0xffff0000, v53
	v_and_b32_e32 v52, 0xffff0000, v52
	v_pk_fma_f32 v[46:47], s[10:11], v[46:47], v[44:45] neg_lo:[1,0,0] neg_hi:[1,0,0]
	v_pk_fma_f32 v[44:45], s[10:11], v[52:53], v[54:55] neg_lo:[1,0,0] neg_hi:[1,0,0]
	s_waitcnt vmcnt(2)
	v_lshlrev_b32_e32 v57, 16, v41
	v_pk_mul_f32 v[52:53], v[44:45], v[44:45]
	v_lshlrev_b32_e32 v56, 16, v40
	v_pk_fma_f32 v[88:89], v[46:47], v[46:47], v[52:53]
	ds_read_b128 v[52:55], v64 offset:1024
	v_and_b32_e32 v41, 0xffff0000, v41
	v_and_b32_e32 v40, 0xffff0000, v40
	s_waitcnt vmcnt(0)
	v_lshlrev_b32_e32 v65, 16, v25
	v_and_b32_e32 v25, 0xffff0000, v25
	s_waitcnt lgkmcnt(0)
	v_and_b32_e32 v61, 0xffff0000, v53
	v_and_b32_e32 v60, 0xffff0000, v52
	v_lshlrev_b32_e32 v59, 16, v53
	v_lshlrev_b32_e32 v58, 16, v52
	v_pk_fma_f32 v[40:41], s[10:11], v[60:61], v[40:41] neg_lo:[1,0,0] neg_hi:[1,0,0]
	v_pk_fma_f32 v[52:53], s[10:11], v[58:59], v[56:57] neg_lo:[1,0,0] neg_hi:[1,0,0]
	v_pk_mul_f32 v[56:57], v[40:41], v[40:41]
	v_lshlrev_b32_e32 v59, 16, v55
	v_pk_fma_f32 v[82:83], v[52:53], v[52:53], v[56:57]
	v_lshlrev_b32_e32 v57, 16, v43
	v_lshlrev_b32_e32 v56, 16, v42
	v_lshlrev_b32_e32 v58, 16, v54
	v_pk_fma_f32 v[62:63], s[10:11], v[58:59], v[56:57] neg_lo:[1,0,0] neg_hi:[1,0,0]
	ds_read_b128 v[56:59], v64 offset:2048
	v_and_b32_e32 v43, 0xffff0000, v43
	v_and_b32_e32 v42, 0xffff0000, v42
	v_and_b32_e32 v55, 0xffff0000, v55
	v_and_b32_e32 v54, 0xffff0000, v54
	v_pk_fma_f32 v[60:61], s[10:11], v[54:55], v[42:43] neg_lo:[1,0,0] neg_hi:[1,0,0]
	s_waitcnt lgkmcnt(0)
	v_lshlrev_b32_e32 v55, 16, v57
	v_pk_mul_f32 v[42:43], v[60:61], v[60:61]
	v_lshlrev_b32_e32 v54, 16, v56
	v_pk_fma_f32 v[84:85], v[62:63], v[62:63], v[42:43]
	v_lshlrev_b32_e32 v43, 16, v29
	v_lshlrev_b32_e32 v42, 16, v28
	v_and_b32_e32 v29, 0xffff0000, v29
	v_and_b32_e32 v28, 0xffff0000, v28
	v_and_b32_e32 v67, 0xffff0000, v57
	v_and_b32_e32 v66, 0xffff0000, v56
	v_pk_fma_f32 v[56:57], s[10:11], v[54:55], v[42:43] neg_lo:[1,0,0] neg_hi:[1,0,0]
	v_pk_fma_f32 v[54:55], s[10:11], v[66:67], v[28:29] neg_lo:[1,0,0] neg_hi:[1,0,0]
	v_lshlrev_b32_e32 v43, 16, v59
	v_pk_mul_f32 v[28:29], v[54:55], v[54:55]
	v_lshlrev_b32_e32 v42, 16, v58
	v_pk_fma_f32 v[78:79], v[56:57], v[56:57], v[28:29]
	v_lshlrev_b32_e32 v29, 16, v31
	v_lshlrev_b32_e32 v28, 16, v30
	v_and_b32_e32 v31, 0xffff0000, v31
	v_and_b32_e32 v30, 0xffff0000, v30
	v_and_b32_e32 v67, 0xffff0000, v59
	v_and_b32_e32 v66, 0xffff0000, v58
	v_pk_fma_f32 v[58:59], s[10:11], v[42:43], v[28:29] neg_lo:[1,0,0] neg_hi:[1,0,0]
	v_pk_fma_f32 v[42:43], s[10:11], v[66:67], v[30:31] neg_lo:[1,0,0] neg_hi:[1,0,0]
	v_and_b32_e32 v177, 0xffff0000, v34
	v_pk_mul_f32 v[28:29], v[42:43], v[42:43]
	v_lshlrev_b32_e32 v34, 16, v38
	v_pk_fma_f32 v[80:81], v[58:59], v[58:59], v[28:29]
	ds_read_b128 v[28:31], v64 offset:3072
	v_lshlrev_b32_e32 v64, 16, v24
	v_and_b32_e32 v24, 0xffff0000, v24
	s_waitcnt lgkmcnt(0)
	v_and_b32_e32 v35, 0xffff0000, v38
	s_waitcnt lgkmcnt(0)
	v_lshlrev_b32_e32 v67, 16, v29
	v_lshlrev_b32_e32 v66, 16, v28
	v_and_b32_e32 v29, 0xffff0000, v29
	v_and_b32_e32 v28, 0xffff0000, v28
	v_pk_fma_f32 v[66:67], s[10:11], v[66:67], v[64:65] neg_lo:[1,0,0] neg_hi:[1,0,0]
	v_pk_fma_f32 v[64:65], s[10:11], v[28:29], v[24:25] neg_lo:[1,0,0] neg_hi:[1,0,0]
	v_lshlrev_b32_e32 v29, 16, v31
	v_pk_mul_f32 v[24:25], v[64:65], v[64:65]
	v_lshlrev_b32_e32 v28, 16, v30
	v_pk_fma_f32 v[74:75], v[66:67], v[66:67], v[24:25]
	v_lshlrev_b32_e32 v25, 16, v27
	v_lshlrev_b32_e32 v24, 16, v26
	v_and_b32_e32 v27, 0xffff0000, v27
	v_and_b32_e32 v26, 0xffff0000, v26
	v_and_b32_e32 v31, 0xffff0000, v31
	v_and_b32_e32 v30, 0xffff0000, v30
	v_pk_fma_f32 v[68:69], s[10:11], v[30:31], v[26:27] neg_lo:[1,0,0] neg_hi:[1,0,0]
	v_pk_fma_f32 v[70:71], s[10:11], v[28:29], v[24:25] neg_lo:[1,0,0] neg_hi:[1,0,0]
	v_pk_mul_f32 v[24:25], v[68:69], v[68:69]
	v_lshlrev_b32_e32 v174, 16, v39
	v_pk_fma_f32 v[76:77], v[70:71], v[70:71], v[24:25]
	v_lshlrev_b32_e32 v24, 2, v239
	v_xor_b32_e32 v171, 4, v24
	v_xor_b32_e32 v170, 8, v24
	v_xor_b32_e32 v169, 16, v24
	global_load_dwordx4 v[24:27], v168, s[8:9] offset:16
	global_load_dwordx4 v[28:31], v168, s[8:9]
	global_load_dwordx4 v[200:203], v168, s[8:9] offset:272
	global_load_dwordx4 v[204:207], v168, s[8:9] offset:256
	v_and_b32_e32 v175, 0xffff0000, v39
	v_pk_fma_f32 v[34:35], s[10:11], v[34:35], v[176:177] neg_lo:[1,0,0] neg_hi:[1,0,0]
	v_lshlrev_b32_e32 v176, 16, v33
	v_and_b32_e32 v177, 0xffff0000, v33
	v_lshlrev_b32_e32 v178, 16, v37
	v_and_b32_e32 v179, 0xffff0000, v37
	v_lshlrev_b32_e32 v180, 16, v32
	v_and_b32_e32 v181, 0xffff0000, v32
	v_lshlrev_b32_e32 v32, 16, v36
	v_and_b32_e32 v33, 0xffff0000, v36
	v_pk_fma_f32 v[172:173], s[10:11], v[174:175], v[172:173] neg_lo:[1,0,0] neg_hi:[1,0,0]
	v_pk_fma_f32 v[176:177], s[10:11], v[178:179], v[176:177] neg_lo:[1,0,0] neg_hi:[1,0,0]
	v_pk_fma_f32 v[36:37], s[10:11], v[32:33], v[180:181] neg_lo:[1,0,0] neg_hi:[1,0,0]
	v_pk_mul_f32 v[174:175], v[172:173], v[172:173]
	v_pk_mul_f32 v[178:179], v[176:177], v[176:177]
	v_pk_mul_f32 v[32:33], v[36:37], v[36:37]
	v_pk_mul_f32 v[38:39], v[34:35], v[34:35]
	v_add_f32_e32 v174, v174, v175
	v_add_f32_e32 v175, v178, v179
	v_add_f32_e32 v32, v32, v33
	v_add_f32_e32 v32, v32, v175
	v_add_f32_e32 v33, v38, v39
	v_add_f32_e32 v32, v33, v32
	v_add_f32_e32 v32, v174, v32
	v_add_f32_e32 v32, v32, v86
	v_add_f32_e32 v32, v87, v32
	v_add_f32_e32 v32, v88, v32
	v_add_f32_e32 v32, v89, v32
	s_nop 1
	v_mov_b32_dpp v33, v32 quad_perm:[1,0,3,2] row_mask:0xf bank_mask:0xf
	s_lshl_b64 s[4:5], s[20:21], 1
	v_readlane_b32 s14, v255, 0
	s_add_u32 s4, s14, s4
	v_readlane_b32 s14, v255, 2
	s_waitcnt lgkmcnt(0)
	v_add_f32_e32 v32, v32, v33
	s_nop 1
	v_mov_b32_dpp v33, v32 quad_perm:[2,3,0,1] row_mask:0xf bank_mask:0xf
	s_addc_u32 s5, s14, s5
	s_add_u32 s4, s4, s96
	s_addc_u32 s5, s5, s97
	v_lshl_add_u64 v[72:73], s[4:5], 0, v[212:213]
	s_waitcnt lgkmcnt(0)
	v_add_f32_e32 v32, v32, v33
	s_nop 1
	v_mov_b32_dpp v33, v32 row_half_mirror row_mask:0xf bank_mask:0xf
	v_lshlrev_b32_e32 v86, 16, v18
	v_and_b32_e32 v87, 0xffff0000, v18
	v_lshlrev_b32_e32 v18, 16, v22
	v_lshlrev_b32_e32 v88, 16, v21
	s_waitcnt lgkmcnt(0)
	v_add_f32_e32 v32, v32, v33
	v_fmamk_f32 v32, v32, 0x3c000000, v251
	v_rsq_f32_e32 v32, v32
	v_and_b32_e32 v89, 0xffff0000, v21
	s_mov_b64 s[4:5], 0
	v_mul_f32_e32 v32, v238, v32
	v_pk_mul_f32 v[36:37], v[36:37], v[32:33] op_sel_hi:[1,0]
	v_pk_mul_f32 v[38:39], v[176:177], v[32:33] op_sel_hi:[1,0]
	v_pk_mul_f32 v[34:35], v[34:35], v[32:33] op_sel_hi:[1,0]
	s_waitcnt vmcnt(0)
	v_pk_mul_f32 v[36:37], v[28:29], v[36:37]
	v_pk_mul_f32 v[38:39], v[30:31], v[38:39]
	v_pk_mul_f32 v[34:35], v[24:25], v[34:35]
	v_cvt_pk_bf16_f32 v36, v36, v37
	v_cvt_pk_bf16_f32 v37, v38, v39
	v_cvt_pk_bf16_f32 v38, v34, v35
	v_pk_mul_f32 v[34:35], v[172:173], v[32:33] op_sel_hi:[1,0]
	v_lshlrev_b32_e32 v33, 8, v239
	v_pk_mul_f32 v[34:35], v[26:27], v[34:35]
	v_and_b32_e32 v212, 0x3800, v33
	v_cvt_pk_bf16_f32 v39, v34, v35
	v_lshl_add_u64 v[34:35], v[72:73], 0, v[212:213]
	global_store_dwordx4 v[34:35], v[36:39], off
	v_lshlrev_b32_e32 v172, 16, v16
	v_and_b32_e32 v173, 0xffff0000, v16
	v_lshlrev_b32_e32 v36, 16, v19
	v_and_b32_e32 v37, 0xffff0000, v19
	v_and_b32_e32 v19, 0xffff0000, v22
	v_lshlrev_b32_e32 v38, 16, v23
	v_and_b32_e32 v39, 0xffff0000, v23
	v_pk_fma_f32 v[18:19], s[10:11], v[18:19], v[86:87] neg_lo:[1,0,0] neg_hi:[1,0,0]
	v_lshlrev_b32_e32 v86, 16, v17
	v_and_b32_e32 v87, 0xffff0000, v17
	v_lshlrev_b32_e32 v16, 16, v20
	v_and_b32_e32 v17, 0xffff0000, v20
	v_pk_fma_f32 v[36:37], s[10:11], v[38:39], v[36:37] neg_lo:[1,0,0] neg_hi:[1,0,0]
	v_pk_fma_f32 v[86:87], s[10:11], v[88:89], v[86:87] neg_lo:[1,0,0] neg_hi:[1,0,0]
	v_pk_fma_f32 v[20:21], s[10:11], v[16:17], v[172:173] neg_lo:[1,0,0] neg_hi:[1,0,0]
	v_pk_mul_f32 v[38:39], v[36:37], v[36:37]
	v_pk_mul_f32 v[88:89], v[86:87], v[86:87]
	v_pk_mul_f32 v[16:17], v[20:21], v[20:21]
	v_pk_mul_f32 v[22:23], v[18:19], v[18:19]
	v_add_f32_e32 v33, v38, v39
	v_add_f32_e32 v38, v88, v89
	v_add_f32_e32 v16, v16, v17
	v_add_f32_e32 v16, v16, v38
	v_add_f32_e32 v17, v22, v23
	v_add_f32_e32 v16, v17, v16
	v_add_f32_e32 v16, v33, v16
	v_add_f32_e32 v16, v16, v82
	v_add_f32_e32 v16, v83, v16
	v_add_f32_e32 v16, v84, v16
	v_add_f32_e32 v16, v85, v16
	s_nop 1
	v_mov_b32_dpp v17, v16 quad_perm:[1,0,3,2] row_mask:0xf bank_mask:0xf
	v_lshlrev_b32_e32 v38, 16, v13
	v_and_b32_e32 v39, 0xffff0000, v13
	v_lshlrev_b32_e32 v82, 16, v8
	v_and_b32_e32 v83, 0xffff0000, v8
	s_waitcnt lgkmcnt(0)
	v_add_f32_e32 v16, v16, v17
	s_nop 1
	v_mov_b32_dpp v17, v16 quad_perm:[2,3,0,1] row_mask:0xf bank_mask:0xf
	v_lshlrev_b32_e32 v8, 16, v12
	s_waitcnt lgkmcnt(0)
	v_add_f32_e32 v16, v16, v17
	s_nop 1
	v_mov_b32_dpp v17, v16 row_half_mirror row_mask:0xf bank_mask:0xf
	s_waitcnt lgkmcnt(0)
	v_add_f32_e32 v16, v16, v17
	v_fmamk_f32 v16, v16, 0x3c000000, v251
	v_rsq_f32_e32 v16, v16
	s_nop 0
	v_mul_f32_e32 v16, v238, v16
	v_pk_mul_f32 v[20:21], v[20:21], v[16:17] op_sel_hi:[1,0]
	v_pk_mul_f32 v[22:23], v[86:87], v[16:17] op_sel_hi:[1,0]
	v_pk_mul_f32 v[18:19], v[18:19], v[16:17] op_sel_hi:[1,0]
	v_pk_mul_f32 v[20:21], v[28:29], v[20:21]
	v_pk_mul_f32 v[22:23], v[30:31], v[22:23]
	v_pk_mul_f32 v[18:19], v[24:25], v[18:19]
	v_cvt_pk_bf16_f32 v20, v20, v21
	v_cvt_pk_bf16_f32 v21, v22, v23
	v_cvt_pk_bf16_f32 v22, v18, v19
	v_pk_mul_f32 v[18:19], v[36:37], v[16:17] op_sel_hi:[1,0]
	s_nop 0
	v_pk_mul_f32 v[18:19], v[26:27], v[18:19]
	s_nop 0
	v_cvt_pk_bf16_f32 v23, v18, v19
	v_or_b32_e32 v18, 0x4000, v212
	v_mov_b32_e32 v19, v213
	v_lshl_add_u64 v[36:37], v[72:73], 0, v[18:19]
	global_store_dwordx4 v[36:37], v[20:23], off
	v_lshlrev_b32_e32 v36, 16, v10
	v_and_b32_e32 v37, 0xffff0000, v10
	v_lshlrev_b32_e32 v20, 16, v11
	v_and_b32_e32 v21, 0xffff0000, v11
	v_lshlrev_b32_e32 v10, 16, v14
	v_and_b32_e32 v11, 0xffff0000, v14
	v_lshlrev_b32_e32 v22, 16, v15
	v_and_b32_e32 v23, 0xffff0000, v15
	v_pk_fma_f32 v[10:11], s[10:11], v[10:11], v[36:37] neg_lo:[1,0,0] neg_hi:[1,0,0]
	v_lshlrev_b32_e32 v36, 16, v9
	v_and_b32_e32 v37, 0xffff0000, v9
	v_and_b32_e32 v9, 0xffff0000, v12
	v_pk_fma_f32 v[20:21], s[10:11], v[22:23], v[20:21] neg_lo:[1,0,0] neg_hi:[1,0,0]
	v_pk_fma_f32 v[36:37], s[10:11], v[38:39], v[36:37] neg_lo:[1,0,0] neg_hi:[1,0,0]
	v_pk_fma_f32 v[12:13], s[10:11], v[8:9], v[82:83] neg_lo:[1,0,0] neg_hi:[1,0,0]
	v_pk_mul_f32 v[22:23], v[20:21], v[20:21]
	v_pk_mul_f32 v[38:39], v[36:37], v[36:37]
	v_pk_mul_f32 v[8:9], v[12:13], v[12:13]
	v_pk_mul_f32 v[14:15], v[10:11], v[10:11]
	v_add_f32_e32 v17, v22, v23
	v_add_f32_e32 v22, v38, v39
	v_add_f32_e32 v8, v8, v9
	v_add_f32_e32 v8, v8, v22
	v_add_f32_e32 v9, v14, v15
	v_add_f32_e32 v8, v9, v8
	v_add_f32_e32 v8, v17, v8
	v_add_f32_e32 v8, v8, v78
	v_add_f32_e32 v8, v79, v8
	v_add_f32_e32 v8, v80, v8
	v_add_f32_e32 v8, v81, v8
	s_nop 1
	v_mov_b32_dpp v9, v8 quad_perm:[1,0,3,2] row_mask:0xf bank_mask:0xf
	v_lshlrev_b32_e32 v22, 16, v5
	v_and_b32_e32 v23, 0xffff0000, v5
	s_waitcnt lgkmcnt(0)
	v_add_f32_e32 v8, v8, v9
	s_nop 1
	v_mov_b32_dpp v9, v8 quad_perm:[2,3,0,1] row_mask:0xf bank_mask:0xf
	s_waitcnt lgkmcnt(0)
	v_add_f32_e32 v8, v8, v9
	s_nop 1
	v_mov_b32_dpp v9, v8 row_half_mirror row_mask:0xf bank_mask:0xf
	s_waitcnt lgkmcnt(0)
	v_add_f32_e32 v8, v8, v9
	v_fmamk_f32 v8, v8, 0x3c000000, v251
	v_rsq_f32_e32 v8, v8
	s_nop 0
	v_mul_f32_e32 v8, v238, v8
	v_pk_mul_f32 v[12:13], v[12:13], v[8:9] op_sel_hi:[1,0]
	v_pk_mul_f32 v[14:15], v[36:37], v[8:9] op_sel_hi:[1,0]
	v_pk_mul_f32 v[10:11], v[10:11], v[8:9] op_sel_hi:[1,0]
	v_pk_mul_f32 v[12:13], v[28:29], v[12:13]
	v_pk_mul_f32 v[14:15], v[30:31], v[14:15]
	v_pk_mul_f32 v[10:11], v[24:25], v[10:11]
	v_cvt_pk_bf16_f32 v12, v12, v13
	v_cvt_pk_bf16_f32 v13, v14, v15
	v_cvt_pk_bf16_f32 v14, v10, v11
	v_pk_mul_f32 v[10:11], v[20:21], v[8:9] op_sel_hi:[1,0]
	v_lshlrev_b32_e32 v36, 16, v0
	v_pk_mul_f32 v[10:11], v[26:27], v[10:11]
	v_and_b32_e32 v37, 0xffff0000, v0
	v_cvt_pk_bf16_f32 v15, v10, v11
	v_or_b32_e32 v10, 0x8000, v212
	v_mov_b32_e32 v11, v213
	v_lshl_add_u64 v[20:21], v[72:73], 0, v[10:11]
	global_store_dwordx4 v[20:21], v[12:15], off
	v_lshlrev_b32_e32 v20, 16, v2
	v_and_b32_e32 v21, 0xffff0000, v2
	v_lshlrev_b32_e32 v12, 16, v3
	v_and_b32_e32 v13, 0xffff0000, v3
	v_lshlrev_b32_e32 v2, 16, v6
	v_and_b32_e32 v3, 0xffff0000, v6
	v_lshlrev_b32_e32 v14, 16, v7
	v_and_b32_e32 v15, 0xffff0000, v7
	v_pk_fma_f32 v[2:3], s[10:11], v[2:3], v[20:21] neg_lo:[1,0,0] neg_hi:[1,0,0]
	v_lshlrev_b32_e32 v20, 16, v1
	v_and_b32_e32 v21, 0xffff0000, v1
	v_lshlrev_b32_e32 v0, 16, v4
	v_and_b32_e32 v1, 0xffff0000, v4
	v_pk_fma_f32 v[12:13], s[10:11], v[14:15], v[12:13] neg_lo:[1,0,0] neg_hi:[1,0,0]
	v_pk_fma_f32 v[20:21], s[10:11], v[22:23], v[20:21] neg_lo:[1,0,0] neg_hi:[1,0,0]
	v_pk_fma_f32 v[0:1], s[10:11], v[0:1], v[36:37] neg_lo:[1,0,0] neg_hi:[1,0,0]
	v_pk_mul_f32 v[14:15], v[12:13], v[12:13]
	v_pk_mul_f32 v[22:23], v[20:21], v[20:21]
	v_pk_mul_f32 v[4:5], v[0:1], v[0:1]
	v_pk_mul_f32 v[6:7], v[2:3], v[2:3]
	v_add_f32_e32 v9, v14, v15
	v_add_f32_e32 v14, v22, v23
	v_add_f32_e32 v4, v4, v5
	v_add_f32_e32 v4, v4, v14
	v_add_f32_e32 v5, v6, v7
	v_add_f32_e32 v4, v5, v4
	v_add_f32_e32 v4, v9, v4
	v_add_f32_e32 v4, v4, v74
	v_add_f32_e32 v4, v75, v4
	v_add_f32_e32 v4, v76, v4
	v_add_f32_e32 v4, v77, v4
	s_nop 1
	v_mov_b32_dpp v5, v4 quad_perm:[1,0,3,2] row_mask:0xf bank_mask:0xf
	v_or_b32_e32 v212, 0xc000, v212
	s_waitcnt lgkmcnt(0)
	v_add_f32_e32 v4, v4, v5
	s_nop 1
	v_mov_b32_dpp v5, v4 quad_perm:[2,3,0,1] row_mask:0xf bank_mask:0xf
	s_waitcnt lgkmcnt(0)
	v_add_f32_e32 v4, v4, v5
	s_nop 1
	v_mov_b32_dpp v5, v4 row_half_mirror row_mask:0xf bank_mask:0xf
	s_waitcnt lgkmcnt(0)
	v_add_f32_e32 v4, v4, v5
	v_fmamk_f32 v4, v4, 0x3c000000, v251
	v_rsq_f32_e32 v4, v4
	s_nop 0
	v_mul_f32_e32 v22, v238, v4
	v_pk_mul_f32 v[0:1], v[0:1], v[22:23] op_sel_hi:[1,0]
	v_pk_mul_f32 v[4:5], v[20:21], v[22:23] op_sel_hi:[1,0]
	v_pk_mul_f32 v[0:1], v[28:29], v[0:1]
	v_pk_mul_f32 v[4:5], v[30:31], v[4:5]
	v_cvt_pk_bf16_f32 v0, v0, v1
	v_cvt_pk_bf16_f32 v1, v4, v5
	v_pk_mul_f32 v[2:3], v[2:3], v[22:23] op_sel_hi:[1,0]
	v_pk_mul_f32 v[4:5], v[12:13], v[22:23] op_sel_hi:[1,0]
	v_pk_mul_f32 v[2:3], v[24:25], v[2:3]
	v_pk_mul_f32 v[4:5], v[26:27], v[4:5]
	v_cvt_pk_bf16_f32 v2, v2, v3
	v_cvt_pk_bf16_f32 v3, v4, v5
	v_lshl_add_u64 v[4:5], v[72:73], 0, v[212:213]
	global_store_dwordx4 v[4:5], v[0:3], off
	v_mov_b64_e32 v[4:5], v[204:205]
	v_mov_b64_e32 v[6:7], v[206:207]
	v_mov_b64_e32 v[0:1], v[200:201]
	v_mov_b64_e32 v[2:3], v[202:203]
	v_mov_b32_e32 v12, v50
	v_mov_b32_e32 v13, v48
	v_mov_b32_e32 v48, v51
	v_pk_mul_f32 v[12:13], v[12:13], v[32:33] op_sel_hi:[1,0]
	v_pk_mul_f32 v[14:15], v[48:49], v[32:33] op_sel_hi:[1,0]
	v_lshl_add_u64 v[20:21], v[72:73], 0, s[44:45]
	v_pk_mul_f32 v[12:13], v[12:13], v[4:5]
	v_pk_mul_f32 v[14:15], v[14:15], v[6:7]
	v_cvt_pk_bf16_f32 v12, v12, v13
	v_cvt_pk_bf16_f32 v13, v14, v15
	v_mov_b32_e32 v14, v46
	v_mov_b32_e32 v15, v44
	v_mov_b32_e32 v44, v47
	v_pk_mul_f32 v[14:15], v[14:15], v[32:33] op_sel_hi:[1,0]
	v_pk_mul_f32 v[24:25], v[44:45], v[32:33] op_sel_hi:[1,0]
	v_pk_mul_f32 v[14:15], v[14:15], v[0:1]
	v_pk_mul_f32 v[24:25], v[24:25], v[2:3]
	v_cvt_pk_bf16_f32 v14, v14, v15
	v_cvt_pk_bf16_f32 v15, v24, v25
	global_store_dwordx4 v[34:35], v[12:15], off offset:128
	s_nop 1
	v_mov_b32_e32 v12, v52
	v_mov_b32_e32 v13, v40
	v_mov_b32_e32 v40, v53
	v_pk_mul_f32 v[12:13], v[12:13], v[16:17] op_sel_hi:[1,0]
	v_pk_mul_f32 v[14:15], v[40:41], v[16:17] op_sel_hi:[1,0]
	v_pk_mul_f32 v[12:13], v[12:13], v[4:5]
	v_pk_mul_f32 v[14:15], v[14:15], v[6:7]
	v_cvt_pk_bf16_f32 v12, v12, v13
	v_cvt_pk_bf16_f32 v13, v14, v15
	v_mov_b32_e32 v14, v62
	v_mov_b32_e32 v15, v60
	v_mov_b32_e32 v60, v63
	v_pk_mul_f32 v[14:15], v[14:15], v[16:17] op_sel_hi:[1,0]
	v_pk_mul_f32 v[16:17], v[60:61], v[16:17] op_sel_hi:[1,0]
	v_pk_mul_f32 v[14:15], v[14:15], v[0:1]
	v_pk_mul_f32 v[16:17], v[16:17], v[2:3]
	v_cvt_pk_bf16_f32 v14, v14, v15
	v_cvt_pk_bf16_f32 v15, v16, v17
	v_lshl_add_u64 v[16:17], v[20:21], 0, v[18:19]
	global_store_dwordx4 v[16:17], v[12:15], off
	s_nop 1
	v_mov_b32_e32 v12, v56
	v_mov_b32_e32 v13, v54
	v_mov_b32_e32 v54, v57
	v_pk_mul_f32 v[12:13], v[12:13], v[8:9] op_sel_hi:[1,0]
	v_pk_mul_f32 v[14:15], v[54:55], v[8:9] op_sel_hi:[1,0]
	v_pk_mul_f32 v[12:13], v[12:13], v[4:5]
	v_pk_mul_f32 v[14:15], v[14:15], v[6:7]
	v_cvt_pk_bf16_f32 v12, v12, v13
	v_cvt_pk_bf16_f32 v13, v14, v15
	v_mov_b32_e32 v14, v58
	v_mov_b32_e32 v15, v42
	v_mov_b32_e32 v42, v59
	v_pk_mul_f32 v[14:15], v[14:15], v[8:9] op_sel_hi:[1,0]
	v_pk_mul_f32 v[8:9], v[42:43], v[8:9] op_sel_hi:[1,0]
	v_pk_mul_f32 v[14:15], v[14:15], v[0:1]
	v_pk_mul_f32 v[8:9], v[8:9], v[2:3]
	v_cvt_pk_bf16_f32 v14, v14, v15
	v_cvt_pk_bf16_f32 v15, v8, v9
	v_lshl_add_u64 v[8:9], v[20:21], 0, v[10:11]
	global_store_dwordx4 v[8:9], v[12:15], off
	v_mov_b32_e32 v8, v66
	v_mov_b32_e32 v9, v64
	v_pk_mul_f32 v[8:9], v[8:9], v[22:23] op_sel_hi:[1,0]
	v_mov_b32_e32 v64, v67
	v_pk_mul_f32 v[4:5], v[8:9], v[4:5]
	v_pk_mul_f32 v[8:9], v[64:65], v[22:23] op_sel_hi:[1,0]
	v_cvt_pk_bf16_f32 v4, v4, v5
	v_pk_mul_f32 v[6:7], v[8:9], v[6:7]
	s_nop 0
	v_cvt_pk_bf16_f32 v5, v6, v7
	v_mov_b32_e32 v6, v70
	v_mov_b32_e32 v7, v68
	v_pk_mul_f32 v[6:7], v[6:7], v[22:23] op_sel_hi:[1,0]
	v_mov_b32_e32 v68, v71
	v_pk_mul_f32 v[0:1], v[6:7], v[0:1]
	s_nop 0
	v_cvt_pk_bf16_f32 v6, v0, v1
	v_pk_mul_f32 v[0:1], v[68:69], v[22:23] op_sel_hi:[1,0]
	s_nop 0
	v_pk_mul_f32 v[0:1], v[0:1], v[2:3]
	s_nop 0
	v_cvt_pk_bf16_f32 v7, v0, v1
	v_lshl_add_u64 v[0:1], v[20:21], 0, v[212:213]
	global_store_dwordx4 v[0:1], v[4:7], off
